# stagger half the WGs by 8us at p8 entry (re-measure)
# speedup vs baseline: 1.0080x; 1.0080x over previous
;     __device__ bool next(int i, Unit& u) const {
;         const int nr = (nwg + G - 1) / G; if (i >= nr) return false;
;         const long L = (long)(rev ? nr - 1 - i : i) * G + c; if (L >= nwg) return false;
;         int wgid = (int)L; { const int q = nwg / NXCD, r = nwg % NXCD, xcd = wgid % NXCD, off = wgid / NXCD; wgid = (xcd < r ? xcd * (q + 1) : r * (q + 1) + (xcd - r) * q) + off; }
;         const int nig = WGM * nN, gid = wgid / nig, fm = gid * WGM, gsz = (nM - fm) < WGM ? (nM - fm) : WGM;
;         u.pm = fm + ((wgid % nig) % gsz); u.pn = (wgid % nig) / gsz; return true;
; __global__ void __launch_bounds__(512, 2) fwd_kernel(Params p) {
;     ...
;         case 8: { pg8::Gemm g{TB, Wt_up, M, FF, D, nullptr, nullptr}; pg8::StaticOrder S; S.init(M, FF, G, bid); EpiB<1> E{HB, FF, 1.f, nullptr, Fold{ST1, CSB + CS_UP, FF}}; pg8::gemm_phase<EpiB<1>>(lds, g, S, E, tid); } break;
.LBB0_152:
	s_andn2_b64 vcc, exec, s[0:1]
	s_cbranch_vccnz .LBB0_182
	v_readlane_b32 s0, v251, 28
	s_cmpk_lt_i32 s0, 0x800
	v_readlane_b32 s4, v250, 44
	s_cselect_b64 s[0:1], -1, 0
	v_readlane_b32 s5, v250, 45
	s_and_b64 s[0:1], s[4:5], s[0:1]
	s_andn2_b64 vcc, exec, s[0:1]
	v_readfirstlane_b32 s12, v210
	s_cbranch_vccnz .LBB0_182
	v_readlane_b32 s1, v251, 28
	s_bitcmp1_b32 s1, 3
	s_cbranch_scc0 .Lstag_skip_p8
	s_sleep 127
	s_sleep 127
.Lstag_skip_p8:
	s_ashr_i32 s33, s1, 31
	s_lshr_b32 s0, s33, 29
	s_add_i32 s2, s1, s0
	s_and_b32 s0, s2, -8
	s_sub_i32 s4, s1, s0
	s_cmp_gt_i32 s4, -1
	s_mov_b64 s[0:1], -1
	s_cbranch_scc0 .LBB0_156
	s_lshl_b32 s5, s4, 8
	s_mov_b64 s[0:1], 0
